# nt hint on the read-once gate loads of the P3 epilogue (EpiD in SchedA/SchedB) so they do not displace GEMM panels in L2
# speedup vs baseline: 1.0120x; 1.0092x over previous
; __device__ __forceinline__ float bf_lo(unsigned w) { return __uint_as_float(w << 16); }
; __device__ __forceinline__ float bf_hi(unsigned w) { return __uint_as_float(w & 0xffff0000u); }
;     __device__ __forceinline__ bool operator()(f32x4 (&acc)[2][2][4][2], const Unit& u, int wr, int wc, int fr, int fq) const {
;         const int r0 = u.pm * BM + wr * 64 + fr, c0 = u.pn * BM + wc * 32 + fq * 8;
;         const bf16_t* S = u.kh ? SGB : SGR;
; #pragma unroll
;         for (int ai = 0; ai < 2; ++ai)
; #pragma unroll
;             for (int m = 0; m < 4; ++m) { const size_t off = (size_t)(r0 + ai * HALF + m * 16) * D + c0;
; #pragma unroll
;                 for (int bj = 0; bj < 2; ++bj) { const u32x4 s = *(const u32x4*)(S + off + bj * HALF);
;                     f32x4 v0 = acc[ai][bj][m][0], v1 = acc[ai][bj][m][1];
;                     v0[0] *= bf_lo(s.x); v0[1] *= bf_hi(s.x); v0[2] *= bf_lo(s.y); v0[3] *= bf_hi(s.y);
;                     v1[0] *= bf_lo(s.z); v1[1] *= bf_hi(s.z); v1[2] *= bf_lo(s.w); v1[3] *= bf_hi(s.w);
;                     acc[ai][bj][m][0] = v0; acc[ai][bj][m][1] = v1; } }
.Lkepi_sa:
	s_cmp_lg_u32 s65, 0
	s_cselect_b64 s[42:43], -1, 0
	s_cmp_eq_u32 s65, 0
	s_cselect_b64 s[0:1], -1, 0
	s_and_b64 vcc, s[0:1], exec
	v_lshl_add_u32 v160, s64, 8, v1
	v_lshl_or_b32 v158, s66, 8, v173
	s_cselect_b32 s0, s5, s15
	s_cselect_b32 s1, s4, s14
	v_mov_b32_e32 v130, s1
	v_mov_b32_e32 v131, s0
	v_ashrrev_i32_e32 v159, 31, v158
	v_ashrrev_i32_e32 v161, 31, v160
	v_lshl_add_u64 v[170:171], v[158:159], 1, v[130:131]
	v_lshlrev_b64 v[130:131], 12, v[160:161]
	v_or_b32_e32 v162, 16, v160
	v_lshl_add_u64 v[130:131], v[170:171], 0, v[130:131]
	v_ashrrev_i32_e32 v163, 31, v162
	v_mov_b64_e32 v[228:229], v[130:131]
	global_load_dwordx4 v[142:145], v[130:131], off nt
	global_load_dwordx4 v[176:179], v[130:131], off offset:256 nt
	v_lshlrev_b64 v[130:131], 12, v[162:163]
	v_or_b32_e32 v164, 32, v160
	v_lshl_add_u64 v[130:131], v[170:171], 0, v[130:131]
	v_ashrrev_i32_e32 v165, 31, v164
	global_load_dwordx4 v[180:183], v[130:131], off nt
	global_load_dwordx4 v[184:187], v[130:131], off offset:256 nt
	v_lshlrev_b64 v[130:131], 12, v[164:165]
	v_lshl_add_u64 v[130:131], v[170:171], 0, v[130:131]
	global_load_dwordx4 v[192:195], v[130:131], off nt
	global_load_dwordx4 v[196:199], v[130:131], off offset:256 nt
	v_or_b32_e32 v166, 48, v160
	v_add_u32_e32 v168, 0x80, v160
	v_ashrrev_i32_e32 v167, 31, v166
	v_ashrrev_i32_e32 v169, 31, v168
	v_lshlrev_b64 v[130:131], 12, v[166:167]
	v_lshlrev_b64 v[132:133], 12, v[168:169]
	v_lshl_add_u64 v[130:131], v[170:171], 0, v[130:131]
	v_lshl_add_u64 v[134:135], v[170:171], 0, v[132:133]
	global_load_dwordx4 v[200:203], v[130:131], off nt
	global_load_dwordx4 v[138:141], v[130:131], off offset:256 nt
	s_nop 0
	global_load_dwordx4 v[130:133], v[134:135], off nt
	s_nop 0
	global_load_dwordx4 v[134:137], v[134:135], off offset:256 nt
	s_mov_b64 s[0:1], 0x90000
	v_lshl_add_u64 v[226:227], v[228:229], 0, s[0:1]
	global_load_dwordx4 v[232:235], v[226:227], off nt
	global_load_dwordx4 v[236:239], v[226:227], off offset:256 nt
	s_mov_b64 s[0:1], 0xa0000
	v_lshl_add_u64 v[226:227], v[228:229], 0, s[0:1]
	global_load_dwordx4 v[240:243], v[226:227], off nt
	global_load_dwordx4 v[244:247], v[226:227], off offset:256 nt
	s_mov_b64 s[0:1], 0xb0000
	v_lshl_add_u64 v[226:227], v[228:229], 0, s[0:1]
	global_load_dwordx4 v[248:251], v[226:227], off nt
	global_load_dwordx4 v[252:255], v[226:227], off offset:256 nt
	s_waitcnt vmcnt(0)
	v_lshlrev_b32_e32 v188, 16, v142
	v_and_b32_e32 v189, 0xffff0000, v142
	v_lshlrev_b32_e32 v142, 16, v143
	v_and_b32_e32 v143, 0xffff0000, v143
	v_pk_mul_f32 v[128:129], v[128:129], v[142:143]
	v_lshlrev_b32_e32 v204, 16, v144
	v_and_b32_e32 v205, 0xffff0000, v144
	v_lshlrev_b32_e32 v144, 16, v145
	v_lshlrev_b32_e32 v142, 16, v192
	v_and_b32_e32 v143, 0xffff0000, v192
	v_pk_mul_f32 v[110:111], v[110:111], v[142:143]
	v_lshlrev_b32_e32 v142, 16, v193
	v_and_b32_e32 v143, 0xffff0000, v193
	v_pk_mul_f32 v[112:113], v[112:113], v[142:143]
	v_add_u32_e32 v142, 0x90, v160
	v_and_b32_e32 v145, 0xffff0000, v145
	v_ashrrev_i32_e32 v143, 31, v142
	v_lshlrev_b32_e32 v210, 16, v180
	v_and_b32_e32 v211, 0xffff0000, v180
	v_lshlrev_b32_e32 v180, 16, v181
	v_and_b32_e32 v181, 0xffff0000, v181
	v_pk_mul_f32 v[124:125], v[124:125], v[144:145]
	v_lshlrev_b64 v[144:145], 12, v[142:143]
	v_lshlrev_b32_e32 v206, 16, v176
	v_and_b32_e32 v207, 0xffff0000, v176
	v_lshlrev_b32_e32 v176, 16, v177
	v_and_b32_e32 v177, 0xffff0000, v177
	v_lshlrev_b32_e32 v208, 16, v178
	v_and_b32_e32 v209, 0xffff0000, v178
	v_lshlrev_b32_e32 v178, 16, v179
	v_and_b32_e32 v179, 0xffff0000, v179
	v_pk_mul_f32 v[120:121], v[120:121], v[180:181]
	v_lshl_add_u64 v[144:145], v[170:171], 0, v[144:145]
	v_lshlrev_b32_e32 v180, 16, v194
	v_and_b32_e32 v181, 0xffff0000, v194
	v_pk_mul_f32 v[96:97], v[96:97], v[176:177]
	v_pk_mul_f32 v[92:93], v[92:93], v[178:179]
	v_mov_b64_e32 v[176:177], v[232:233]
	v_mov_b64_e32 v[178:179], v[234:235]
	v_pk_mul_f32 v[106:107], v[106:107], v[180:181]
	v_lshlrev_b32_e32 v180, 16, v195
	v_and_b32_e32 v181, 0xffff0000, v195
	v_lshlrev_b32_e32 v212, 16, v182
	v_and_b32_e32 v213, 0xffff0000, v182
	v_lshlrev_b32_e32 v182, 16, v183
	v_and_b32_e32 v183, 0xffff0000, v183
	v_pk_mul_f32 v[108:109], v[108:109], v[180:181]
	v_lshlrev_b32_e32 v180, 16, v196
	v_and_b32_e32 v181, 0xffff0000, v196
	v_pk_mul_f32 v[116:117], v[116:117], v[182:183]
	v_pk_mul_f32 v[78:79], v[78:79], v[180:181]
	v_mov_b64_e32 v[180:181], v[236:237]
	v_mov_b64_e32 v[182:183], v[238:239]
	v_lshlrev_b32_e32 v144, 16, v198
	v_and_b32_e32 v145, 0xffff0000, v198
	v_pk_mul_f32 v[74:75], v[74:75], v[144:145]
	v_lshlrev_b32_e32 v144, 16, v199
	v_and_b32_e32 v145, 0xffff0000, v199
	v_lshlrev_b32_e32 v214, 16, v184
	v_and_b32_e32 v215, 0xffff0000, v184
	v_lshlrev_b32_e32 v184, 16, v185
	v_and_b32_e32 v185, 0xffff0000, v185
	v_pk_mul_f32 v[76:77], v[76:77], v[144:145]
	v_add_u32_e32 v144, 0xa0, v160
	v_pk_mul_f32 v[88:89], v[88:89], v[184:185]
	v_lshlrev_b32_e32 v184, 16, v197
	v_and_b32_e32 v185, 0xffff0000, v197
	v_ashrrev_i32_e32 v145, 31, v144
	v_pk_mul_f32 v[80:81], v[80:81], v[184:185]
	v_lshlrev_b64 v[184:185], 12, v[144:145]
	v_lshlrev_b32_e32 v216, 16, v186
	v_and_b32_e32 v217, 0xffff0000, v186
	v_lshlrev_b32_e32 v186, 16, v187
	v_and_b32_e32 v187, 0xffff0000, v187
	v_pk_mul_f32 v[126:127], v[126:127], v[188:189]
	v_lshl_add_u64 v[188:189], v[170:171], 0, v[184:185]
	v_pk_mul_f32 v[84:85], v[84:85], v[186:187]
	v_mov_b64_e32 v[184:185], v[240:241]
	v_mov_b64_e32 v[186:187], v[242:243]
	v_lshlrev_b32_e32 v192, 16, v200
	v_and_b32_e32 v193, 0xffff0000, v200
	v_pk_mul_f32 v[102:103], v[102:103], v[192:193]
	v_lshlrev_b32_e32 v192, 16, v201
; __device__ __forceinline__ float bf_lo(unsigned w) { return __uint_as_float(w << 16); }
; __device__ __forceinline__ float bf_hi(unsigned w) { return __uint_as_float(w & 0xffff0000u); }
;     __device__ __forceinline__ bool operator()(f32x4 (&acc)[2][2][4][2], const Unit& u, int wr, int wc, int fr, int fq) const {
;     ...
;             for (int m = 0; m < 4; ++m) { const size_t off = (size_t)(r0 + ai * HALF + m * 16) * D + c0;
; #pragma unroll
;                 for (int bj = 0; bj < 2; ++bj) { const u32x4 s = *(const u32x4*)(S + off + bj * HALF);
;                     f32x4 v0 = acc[ai][bj][m][0], v1 = acc[ai][bj][m][1];
;                     v0[0] *= bf_lo(s.x); v0[1] *= bf_hi(s.x); v0[2] *= bf_lo(s.y); v0[3] *= bf_hi(s.y);
;                     v1[0] *= bf_lo(s.z); v1[1] *= bf_hi(s.z); v1[2] *= bf_lo(s.w); v1[3] *= bf_hi(s.w);
;                     acc[ai][bj][m][0] = v0; acc[ai][bj][m][1] = v1; } }
	v_and_b32_e32 v193, 0xffff0000, v201
	v_pk_mul_f32 v[104:105], v[104:105], v[192:193]
	v_lshlrev_b32_e32 v192, 16, v202
	v_and_b32_e32 v193, 0xffff0000, v202
	v_pk_mul_f32 v[98:99], v[98:99], v[192:193]
	v_mov_b64_e32 v[192:193], v[244:245]
	v_mov_b64_e32 v[194:195], v[246:247]
	v_lshlrev_b32_e32 v188, 16, v138
	v_and_b32_e32 v189, 0xffff0000, v138
	v_lshlrev_b32_e32 v138, 16, v139
	v_and_b32_e32 v139, 0xffff0000, v139
	v_pk_mul_f32 v[72:73], v[72:73], v[138:139]
	v_add_u32_e32 v138, 0xb0, v160
	v_ashrrev_i32_e32 v139, 31, v138
	v_pk_mul_f32 v[70:71], v[70:71], v[188:189]
	v_lshlrev_b64 v[188:189], 12, v[138:139]
	v_lshlrev_b32_e32 v196, 16, v203
	v_and_b32_e32 v197, 0xffff0000, v203
	v_lshl_add_u64 v[170:171], v[170:171], 0, v[188:189]
	v_pk_mul_f32 v[100:101], v[100:101], v[196:197]
	v_mov_b64_e32 v[196:197], v[248:249]
	v_mov_b64_e32 v[198:199], v[250:251]
	v_mov_b64_e32 v[200:201], v[252:253]
	v_mov_b64_e32 v[202:203], v[254:255]
	v_lshlrev_b32_e32 v188, 16, v140
	v_and_b32_e32 v189, 0xffff0000, v140
	v_lshlrev_b32_e32 v140, 16, v141
	v_and_b32_e32 v141, 0xffff0000, v141
	v_pk_mul_f32 v[68:69], v[68:69], v[140:141]
	v_lshlrev_b32_e32 v140, 16, v130
	v_and_b32_e32 v141, 0xffff0000, v130
	v_lshlrev_b32_e32 v130, 16, v131
	v_and_b32_e32 v131, 0xffff0000, v131
	v_pk_mul_f32 v[64:65], v[64:65], v[130:131]
	v_lshlrev_b32_e32 v130, 16, v132
	v_and_b32_e32 v131, 0xffff0000, v132
	v_pk_mul_f32 v[58:59], v[58:59], v[130:131]
	v_lshlrev_b32_e32 v130, 16, v133
	v_and_b32_e32 v131, 0xffff0000, v133
	v_pk_mul_f32 v[60:61], v[60:61], v[130:131]
	v_lshlrev_b32_e32 v130, 16, v134
	v_and_b32_e32 v131, 0xffff0000, v134
	v_pk_mul_f32 v[30:31], v[30:31], v[130:131]
	v_lshlrev_b32_e32 v130, 16, v135
	v_and_b32_e32 v131, 0xffff0000, v135
	v_pk_mul_f32 v[32:33], v[32:33], v[130:131]
	v_lshlrev_b32_e32 v130, 16, v136
	v_and_b32_e32 v131, 0xffff0000, v136
	v_pk_mul_f32 v[26:27], v[26:27], v[130:131]
	v_lshlrev_b32_e32 v130, 16, v137
	v_and_b32_e32 v131, 0xffff0000, v137
	v_pk_mul_f32 v[28:29], v[28:29], v[130:131]
	s_waitcnt vmcnt(0)
	v_lshlrev_b32_e32 v130, 16, v176
	v_and_b32_e32 v131, 0xffff0000, v176
	v_pk_mul_f32 v[54:55], v[54:55], v[130:131]
	v_lshlrev_b32_e32 v130, 16, v177
	v_and_b32_e32 v131, 0xffff0000, v177
	v_pk_mul_f32 v[56:57], v[56:57], v[130:131]
	v_lshlrev_b32_e32 v130, 16, v178
	v_and_b32_e32 v131, 0xffff0000, v178
	v_pk_mul_f32 v[50:51], v[50:51], v[130:131]
	v_lshlrev_b32_e32 v130, 16, v179
	v_and_b32_e32 v131, 0xffff0000, v179
	v_pk_mul_f32 v[52:53], v[52:53], v[130:131]
	v_lshlrev_b32_e32 v130, 16, v180
	v_and_b32_e32 v131, 0xffff0000, v180
	v_pk_mul_f32 v[22:23], v[22:23], v[130:131]
	v_lshlrev_b32_e32 v130, 16, v181
	v_and_b32_e32 v131, 0xffff0000, v181
	v_pk_mul_f32 v[24:25], v[24:25], v[130:131]
	v_lshlrev_b32_e32 v130, 16, v182
	v_and_b32_e32 v131, 0xffff0000, v182
	v_pk_mul_f32 v[18:19], v[18:19], v[130:131]
	v_lshlrev_b32_e32 v130, 16, v183
	v_and_b32_e32 v131, 0xffff0000, v183
	v_pk_mul_f32 v[20:21], v[20:21], v[130:131]
	v_pk_mul_f32 v[122:123], v[122:123], v[204:205]
	v_pk_mul_f32 v[94:95], v[94:95], v[206:207]
	v_lshlrev_b32_e32 v130, 16, v184
	v_and_b32_e32 v131, 0xffff0000, v184
	v_pk_mul_f32 v[46:47], v[46:47], v[130:131]
	v_lshlrev_b32_e32 v130, 16, v185
	v_and_b32_e32 v131, 0xffff0000, v185
	v_pk_mul_f32 v[48:49], v[48:49], v[130:131]
	v_lshlrev_b32_e32 v130, 16, v186
	v_and_b32_e32 v131, 0xffff0000, v186
	v_pk_mul_f32 v[42:43], v[42:43], v[130:131]
	v_lshlrev_b32_e32 v130, 16, v187
	v_and_b32_e32 v131, 0xffff0000, v187
	v_pk_mul_f32 v[44:45], v[44:45], v[130:131]
	v_lshlrev_b32_e32 v130, 16, v192
	v_and_b32_e32 v131, 0xffff0000, v192
	v_pk_mul_f32 v[14:15], v[14:15], v[130:131]
	v_lshlrev_b32_e32 v130, 16, v193
	v_and_b32_e32 v131, 0xffff0000, v193
	v_pk_mul_f32 v[16:17], v[16:17], v[130:131]
	v_lshlrev_b32_e32 v130, 16, v194
	v_and_b32_e32 v131, 0xffff0000, v194
	v_pk_mul_f32 v[10:11], v[10:11], v[130:131]
	v_lshlrev_b32_e32 v130, 16, v195
	v_and_b32_e32 v131, 0xffff0000, v195
	v_pk_mul_f32 v[12:13], v[12:13], v[130:131]
	v_lshlrev_b32_e32 v130, 16, v196
	v_and_b32_e32 v131, 0xffff0000, v196
	v_pk_mul_f32 v[38:39], v[38:39], v[130:131]
	v_lshlrev_b32_e32 v130, 16, v197
	v_and_b32_e32 v131, 0xffff0000, v197
	v_pk_mul_f32 v[40:41], v[40:41], v[130:131]
	v_lshlrev_b32_e32 v130, 16, v198
	v_and_b32_e32 v131, 0xffff0000, v198
	v_pk_mul_f32 v[34:35], v[34:35], v[130:131]
	v_lshlrev_b32_e32 v130, 16, v199
	v_and_b32_e32 v131, 0xffff0000, v199
	v_pk_mul_f32 v[36:37], v[36:37], v[130:131]
	v_lshlrev_b32_e32 v130, 16, v200
	v_and_b32_e32 v131, 0xffff0000, v200
	v_pk_mul_f32 v[6:7], v[6:7], v[130:131]
	v_lshlrev_b32_e32 v130, 16, v201
	v_and_b32_e32 v131, 0xffff0000, v201
	v_pk_mul_f32 v[8:9], v[8:9], v[130:131]
	v_lshlrev_b32_e32 v130, 16, v202
	v_and_b32_e32 v131, 0xffff0000, v202
	v_pk_mul_f32 v[2:3], v[2:3], v[130:131]
	v_lshlrev_b32_e32 v130, 16, v203
	v_and_b32_e32 v131, 0xffff0000, v203
	v_pk_mul_f32 v[90:91], v[90:91], v[208:209]
	v_pk_mul_f32 v[118:119], v[118:119], v[210:211]
	v_pk_mul_f32 v[114:115], v[114:115], v[212:213]
	v_pk_mul_f32 v[86:87], v[86:87], v[214:215]
	v_pk_mul_f32 v[82:83], v[82:83], v[216:217]
	v_pk_mul_f32 v[66:67], v[66:67], v[188:189]
	v_pk_mul_f32 v[62:63], v[62:63], v[140:141]
	v_pk_mul_f32 v[4:5], v[4:5], v[130:131]
	s_cbranch_vccnz .LBB0_818
; __device__ __forceinline__ unsigned pk_bf16(float lo, float hi) { const f32x2_t v = {lo, hi}; return __builtin_bit_cast(unsigned, __builtin_convertvector(v, bf16x2_t)); }
;     __device__ __forceinline__ bool operator()(f32x4 (&acc)[2][2][4][2], const Unit& u, int wr, int wc, int fr, int fq) const {
;     ...
;             for (int m = 0; m < 4; ++m) { const size_t off = (size_t)(r0 + ai * HALF + m * 16) * LDP + c0;
; #pragma unroll
;                 for (int bj = 0; bj < 2; ++bj) { const f32x4 v0 = acc[ai][bj][m][0], v1 = acc[ai][bj][m][1];
;                     u32x4 w; w.x = pk_bf16(v0[0], v0[1]); w.y = pk_bf16(v0[2], v0[3]); w.z = pk_bf16(v1[0], v1[1]); w.w = pk_bf16(v1[2], v1[3]);
;                     *(u32x4*)(MG + off + bj * HALF) = w; } }
	v_mov_b64_e32 v[134:135], s[12:13]
	v_mad_i64_i32 v[136:137], s[0:1], v160, s60, v[134:135]
	v_lshlrev_b64 v[140:141], 1, v[158:159]
	v_cvt_pk_bf16_f32 v130, v126, v127
	v_cvt_pk_bf16_f32 v131, v128, v129
	v_cvt_pk_bf16_f32 v132, v122, v123
	v_cvt_pk_bf16_f32 v133, v124, v125
	v_lshl_add_u64 v[136:137], v[136:137], 0, v[140:141]
	global_store_dwordx4 v[136:137], v[130:133], off
	s_nop 1
	v_cvt_pk_bf16_f32 v130, v94, v95
	v_cvt_pk_bf16_f32 v131, v96, v97
	v_cvt_pk_bf16_f32 v132, v90, v91
	v_cvt_pk_bf16_f32 v133, v92, v93
	global_store_dwordx4 v[136:137], v[130:133], off offset:256
	v_mad_i64_i32 v[136:137], s[0:1], v162, s60, v[134:135]
	s_nop 0
	v_cvt_pk_bf16_f32 v130, v118, v119
	v_cvt_pk_bf16_f32 v131, v120, v121
	v_cvt_pk_bf16_f32 v132, v114, v115
	v_cvt_pk_bf16_f32 v133, v116, v117
	v_lshl_add_u64 v[136:137], v[136:137], 0, v[140:141]
	global_store_dwordx4 v[136:137], v[130:133], off
	s_nop 1
	v_cvt_pk_bf16_f32 v130, v86, v87
	v_cvt_pk_bf16_f32 v131, v88, v89
	v_cvt_pk_bf16_f32 v132, v82, v83
	v_cvt_pk_bf16_f32 v133, v84, v85
	global_store_dwordx4 v[136:137], v[130:133], off offset:256
	v_mad_i64_i32 v[136:137], s[0:1], v164, s60, v[134:135]
	s_nop 0
	v_cvt_pk_bf16_f32 v130, v110, v111
	v_cvt_pk_bf16_f32 v131, v112, v113
	v_cvt_pk_bf16_f32 v132, v106, v107
	v_cvt_pk_bf16_f32 v133, v108, v109
	v_lshl_add_u64 v[136:137], v[136:137], 0, v[140:141]
	global_store_dwordx4 v[136:137], v[130:133], off
	s_nop 1
	v_cvt_pk_bf16_f32 v130, v78, v79
	v_cvt_pk_bf16_f32 v131, v80, v81
	v_cvt_pk_bf16_f32 v132, v74, v75
	v_cvt_pk_bf16_f32 v133, v76, v77
	global_store_dwordx4 v[136:137], v[130:133], off offset:256
	v_mad_i64_i32 v[136:137], s[0:1], v166, s60, v[134:135]
	s_nop 0
	v_cvt_pk_bf16_f32 v130, v102, v103
	v_cvt_pk_bf16_f32 v131, v104, v105
	v_cvt_pk_bf16_f32 v132, v98, v99
	v_cvt_pk_bf16_f32 v133, v100, v101
	v_lshl_add_u64 v[136:137], v[136:137], 0, v[140:141]
	global_store_dwordx4 v[136:137], v[130:133], off
	s_nop 1
	v_cvt_pk_bf16_f32 v130, v70, v71
	v_cvt_pk_bf16_f32 v131, v72, v73
	v_cvt_pk_bf16_f32 v132, v66, v67
	v_cvt_pk_bf16_f32 v133, v68, v69
	global_store_dwordx4 v[136:137], v[130:133], off offset:256
	v_mad_i64_i32 v[136:137], s[0:1], v168, s60, v[134:135]
	s_nop 0
	v_cvt_pk_bf16_f32 v130, v62, v63
	v_cvt_pk_bf16_f32 v131, v64, v65
	v_cvt_pk_bf16_f32 v132, v58, v59
	v_cvt_pk_bf16_f32 v133, v60, v61
	v_lshl_add_u64 v[136:137], v[136:137], 0, v[140:141]
	global_store_dwordx4 v[136:137], v[130:133], off
	s_nop 1
	v_cvt_pk_bf16_f32 v130, v30, v31
	v_cvt_pk_bf16_f32 v131, v32, v33
	v_cvt_pk_bf16_f32 v132, v26, v27
	v_cvt_pk_bf16_f32 v133, v28, v29
	global_store_dwordx4 v[136:137], v[130:133], off offset:256
	v_mad_i64_i32 v[136:137], s[0:1], v142, s60, v[134:135]
	s_nop 0
	v_cvt_pk_bf16_f32 v130, v54, v55
	v_cvt_pk_bf16_f32 v131, v56, v57
	v_cvt_pk_bf16_f32 v132, v50, v51
	v_cvt_pk_bf16_f32 v133, v52, v53
	v_lshl_add_u64 v[136:137], v[136:137], 0, v[140:141]
	global_store_dwordx4 v[136:137], v[130:133], off
	s_nop 1
	v_cvt_pk_bf16_f32 v130, v22, v23
	v_cvt_pk_bf16_f32 v131, v24, v25
	v_cvt_pk_bf16_f32 v132, v18, v19
	v_cvt_pk_bf16_f32 v133, v20, v21
	global_store_dwordx4 v[136:137], v[130:133], off offset:256
	v_mad_i64_i32 v[136:137], s[0:1], v144, s60, v[134:135]
	s_nop 0
	v_cvt_pk_bf16_f32 v130, v46, v47
	v_cvt_pk_bf16_f32 v131, v48, v49
	v_cvt_pk_bf16_f32 v132, v42, v43
	v_cvt_pk_bf16_f32 v133, v44, v45
	v_lshl_add_u64 v[136:137], v[136:137], 0, v[140:141]
	global_store_dwordx4 v[136:137], v[130:133], off
	v_mad_i64_i32 v[134:135], s[0:1], v138, s60, v[134:135]
	s_nop 0
	v_cvt_pk_bf16_f32 v130, v14, v15
	v_cvt_pk_bf16_f32 v131, v16, v17
	v_cvt_pk_bf16_f32 v132, v10, v11
	v_cvt_pk_bf16_f32 v133, v12, v13
	global_store_dwordx4 v[136:137], v[130:133], off offset:256
	v_lshl_add_u64 v[134:135], v[134:135], 0, v[140:141]
	s_nop 0
	v_cvt_pk_bf16_f32 v130, v38, v39
	v_cvt_pk_bf16_f32 v131, v40, v41
	v_cvt_pk_bf16_f32 v132, v34, v35
	v_cvt_pk_bf16_f32 v133, v36, v37
	global_store_dwordx4 v[134:135], v[130:133], off
	s_nop 1
	v_cvt_pk_bf16_f32 v130, v6, v7
	v_cvt_pk_bf16_f32 v131, v8, v9
	v_cvt_pk_bf16_f32 v132, v2, v3
	v_cvt_pk_bf16_f32 v133, v4, v5
	global_store_dwordx4 v[134:135], v[130:133], off offset:256

; __device__ __forceinline__ float bf_lo(unsigned w) { return __uint_as_float(w << 16); }
; __device__ __forceinline__ float bf_hi(unsigned w) { return __uint_as_float(w & 0xffff0000u); }
;     __device__ __forceinline__ bool operator()(f32x4 (&acc)[2][2][4][2], const Unit& u, int wr, int wc, int fr, int fq) const {
;         const int r0 = u.pm * BM + wr * 64 + fr, c0 = u.pn * BM + wc * 32 + fq * 8;
;         const bf16_t* S = u.kh ? SGB : SGR;
; #pragma unroll
;         for (int ai = 0; ai < 2; ++ai)
; #pragma unroll
;             for (int m = 0; m < 4; ++m) { const size_t off = (size_t)(r0 + ai * HALF + m * 16) * D + c0;
; #pragma unroll
;                 for (int bj = 0; bj < 2; ++bj) { const u32x4 s = *(const u32x4*)(S + off + bj * HALF);
;                     f32x4 v0 = acc[ai][bj][m][0], v1 = acc[ai][bj][m][1];
;                     v0[0] *= bf_lo(s.x); v0[1] *= bf_hi(s.x); v0[2] *= bf_lo(s.y); v0[3] *= bf_hi(s.y);
;                     v1[0] *= bf_lo(s.z); v1[1] *= bf_hi(s.z); v1[2] *= bf_lo(s.w); v1[3] *= bf_hi(s.w);
;                     acc[ai][bj][m][0] = v0; acc[ai][bj][m][1] = v1; } }
.LBB0_902:
	s_cmp_eq_u32 s66, 0
	v_lshl_add_u32 v160, s65, 8, v1
	v_lshl_or_b32 v158, s64, 8, v175
	s_cselect_b32 s0, s4, s14
	s_cselect_b32 s1, s5, s15
	v_mov_b32_e32 v130, s0
	v_mov_b32_e32 v131, s1
	v_ashrrev_i32_e32 v159, 31, v158
	v_ashrrev_i32_e32 v161, 31, v160
	v_lshl_add_u64 v[170:171], v[158:159], 1, v[130:131]
	v_lshlrev_b64 v[130:131], 12, v[160:161]
	v_or_b32_e32 v162, 16, v160
	v_lshl_add_u64 v[130:131], v[170:171], 0, v[130:131]
	v_ashrrev_i32_e32 v163, 31, v162
	global_load_dwordx4 v[142:145], v[130:131], off nt
	global_load_dwordx4 v[178:181], v[130:131], off offset:256 nt
	v_lshlrev_b64 v[130:131], 12, v[162:163]
	v_or_b32_e32 v164, 32, v160
	v_lshl_add_u64 v[130:131], v[170:171], 0, v[130:131]
	v_ashrrev_i32_e32 v165, 31, v164
	global_load_dwordx4 v[182:185], v[130:131], off nt
	global_load_dwordx4 v[186:189], v[130:131], off offset:256 nt
	v_lshlrev_b64 v[130:131], 12, v[164:165]
	v_lshl_add_u64 v[130:131], v[170:171], 0, v[130:131]
	global_load_dwordx4 v[192:195], v[130:131], off nt
	global_load_dwordx4 v[196:199], v[130:131], off offset:256 nt
	v_or_b32_e32 v166, 48, v160
	v_add_u32_e32 v168, 0x80, v160
	v_ashrrev_i32_e32 v167, 31, v166
	v_ashrrev_i32_e32 v169, 31, v168
	v_lshlrev_b64 v[130:131], 12, v[166:167]
	v_lshlrev_b64 v[132:133], 12, v[168:169]
	v_lshl_add_u64 v[130:131], v[170:171], 0, v[130:131]
	v_lshl_add_u64 v[134:135], v[170:171], 0, v[132:133]
	global_load_dwordx4 v[200:203], v[130:131], off nt
	global_load_dwordx4 v[138:141], v[130:131], off offset:256 nt
	s_nop 0
	global_load_dwordx4 v[130:133], v[134:135], off nt
	s_nop 0
	global_load_dwordx4 v[134:137], v[134:135], off offset:256 nt
	s_cmp_lg_u32 s66, 0
	s_waitcnt vmcnt(0)
	v_lshlrev_b32_e32 v172, 16, v142
	v_and_b32_e32 v173, 0xffff0000, v142
	v_lshlrev_b32_e32 v142, 16, v143
	v_and_b32_e32 v143, 0xffff0000, v143
	v_pk_mul_f32 v[128:129], v[128:129], v[142:143]
	v_lshlrev_b32_e32 v204, 16, v144
	v_and_b32_e32 v205, 0xffff0000, v144
	v_lshlrev_b32_e32 v144, 16, v145
	v_lshlrev_b32_e32 v142, 16, v192
	v_and_b32_e32 v143, 0xffff0000, v192
	v_pk_mul_f32 v[110:111], v[110:111], v[142:143]
	v_lshlrev_b32_e32 v142, 16, v193
	v_and_b32_e32 v143, 0xffff0000, v193
	v_pk_mul_f32 v[112:113], v[112:113], v[142:143]
	v_add_u32_e32 v142, 0x90, v160
	v_and_b32_e32 v145, 0xffff0000, v145
	v_ashrrev_i32_e32 v143, 31, v142
	v_pk_mul_f32 v[124:125], v[124:125], v[144:145]
	v_lshlrev_b64 v[144:145], 12, v[142:143]
	v_lshlrev_b32_e32 v206, 16, v178
	v_and_b32_e32 v207, 0xffff0000, v178
	v_lshlrev_b32_e32 v178, 16, v179
	v_and_b32_e32 v179, 0xffff0000, v179
	v_lshlrev_b32_e32 v208, 16, v180
	v_and_b32_e32 v209, 0xffff0000, v180
	v_lshlrev_b32_e32 v180, 16, v181
	v_and_b32_e32 v181, 0xffff0000, v181
	v_lshl_add_u64 v[144:145], v[170:171], 0, v[144:145]
	v_pk_mul_f32 v[96:97], v[96:97], v[178:179]
	v_pk_mul_f32 v[92:93], v[92:93], v[180:181]
	global_load_dwordx4 v[178:181], v[144:145], off nt
	v_lshlrev_b32_e32 v210, 16, v182
	v_and_b32_e32 v211, 0xffff0000, v182
	v_lshlrev_b32_e32 v182, 16, v183
	v_and_b32_e32 v183, 0xffff0000, v183
	v_lshlrev_b32_e32 v212, 16, v184
	v_and_b32_e32 v213, 0xffff0000, v184
	v_lshlrev_b32_e32 v184, 16, v185
	v_and_b32_e32 v185, 0xffff0000, v185
	v_pk_mul_f32 v[126:127], v[126:127], v[172:173]
	v_pk_mul_f32 v[120:121], v[120:121], v[182:183]
	v_pk_mul_f32 v[116:117], v[116:117], v[184:185]
	v_lshlrev_b32_e32 v172, 16, v194
	v_and_b32_e32 v173, 0xffff0000, v194
	global_load_dwordx4 v[182:185], v[144:145], off offset:256 nt
	v_lshlrev_b32_e32 v144, 16, v198
	v_and_b32_e32 v145, 0xffff0000, v198
	v_pk_mul_f32 v[106:107], v[106:107], v[172:173]
	v_lshlrev_b32_e32 v172, 16, v195
	v_and_b32_e32 v173, 0xffff0000, v195
	v_pk_mul_f32 v[74:75], v[74:75], v[144:145]
	v_lshlrev_b32_e32 v144, 16, v199
	v_and_b32_e32 v145, 0xffff0000, v199
	v_pk_mul_f32 v[108:109], v[108:109], v[172:173]
	v_lshlrev_b32_e32 v172, 16, v196
	v_and_b32_e32 v173, 0xffff0000, v196
	v_pk_mul_f32 v[76:77], v[76:77], v[144:145]
	v_add_u32_e32 v144, 0xa0, v160
	v_pk_mul_f32 v[78:79], v[78:79], v[172:173]
	v_lshlrev_b32_e32 v172, 16, v197
	v_and_b32_e32 v173, 0xffff0000, v197
	v_ashrrev_i32_e32 v145, 31, v144
	v_pk_mul_f32 v[80:81], v[80:81], v[172:173]
	v_lshlrev_b64 v[172:173], 12, v[144:145]
	v_lshlrev_b32_e32 v214, 16, v186
	v_and_b32_e32 v215, 0xffff0000, v186
	v_lshlrev_b32_e32 v186, 16, v187
	v_and_b32_e32 v187, 0xffff0000, v187
	v_lshlrev_b32_e32 v216, 16, v188
	v_and_b32_e32 v217, 0xffff0000, v188
	v_lshlrev_b32_e32 v188, 16, v189
	v_and_b32_e32 v189, 0xffff0000, v189
	v_lshl_add_u64 v[172:173], v[170:171], 0, v[172:173]
	v_pk_mul_f32 v[88:89], v[88:89], v[186:187]
	v_pk_mul_f32 v[84:85], v[84:85], v[188:189]
	global_load_dwordx4 v[186:189], v[172:173], off nt
	v_lshlrev_b32_e32 v192, 16, v200
	v_and_b32_e32 v193, 0xffff0000, v200
	v_pk_mul_f32 v[102:103], v[102:103], v[192:193]
	v_lshlrev_b32_e32 v192, 16, v201
	v_and_b32_e32 v193, 0xffff0000, v201
	v_pk_mul_f32 v[104:105], v[104:105], v[192:193]
	v_lshlrev_b32_e32 v192, 16, v202
	v_and_b32_e32 v193, 0xffff0000, v202
	v_pk_mul_f32 v[98:99], v[98:99], v[192:193]
	global_load_dwordx4 v[192:195], v[172:173], off offset:256 nt
	v_lshlrev_b32_e32 v172, 16, v138
	v_and_b32_e32 v173, 0xffff0000, v138
	v_pk_mul_f32 v[70:71], v[70:71], v[172:173]
	v_add_u32_e32 v172, 0xb0, v160
	v_lshlrev_b32_e32 v138, 16, v139
	v_and_b32_e32 v139, 0xffff0000, v139
	v_ashrrev_i32_e32 v173, 31, v172
	v_pk_mul_f32 v[72:73], v[72:73], v[138:139]
	v_lshlrev_b64 v[138:139], 12, v[172:173]
	v_lshlrev_b32_e32 v196, 16, v203
	v_and_b32_e32 v197, 0xffff0000, v203
	v_lshl_add_u64 v[138:139], v[170:171], 0, v[138:139]
	v_pk_mul_f32 v[100:101], v[100:101], v[196:197]
	global_load_dwordx4 v[196:199], v[138:139], off nt
	v_lshlrev_b32_e32 v170, 16, v140
	v_and_b32_e32 v171, 0xffff0000, v140
	v_lshlrev_b32_e32 v140, 16, v141
	v_and_b32_e32 v141, 0xffff0000, v141
	v_pk_mul_f32 v[68:69], v[68:69], v[140:141]
	v_lshlrev_b32_e32 v140, 16, v130
	v_and_b32_e32 v141, 0xffff0000, v130
	v_pk_mul_f32 v[62:63], v[62:63], v[140:141]
	global_load_dwordx4 v[138:141], v[138:139], off offset:256 nt
	v_lshlrev_b32_e32 v130, 16, v131
	v_and_b32_e32 v131, 0xffff0000, v131
	v_pk_mul_f32 v[64:65], v[64:65], v[130:131]
	v_lshlrev_b32_e32 v130, 16, v132
	v_and_b32_e32 v131, 0xffff0000, v132
	v_pk_mul_f32 v[58:59], v[58:59], v[130:131]
	v_lshlrev_b32_e32 v130, 16, v133
	v_and_b32_e32 v131, 0xffff0000, v133
	v_pk_mul_f32 v[60:61], v[60:61], v[130:131]
	v_lshlrev_b32_e32 v130, 16, v134
	v_and_b32_e32 v131, 0xffff0000, v134
	v_pk_mul_f32 v[30:31], v[30:31], v[130:131]
	v_lshlrev_b32_e32 v130, 16, v135
	v_and_b32_e32 v131, 0xffff0000, v135
	v_pk_mul_f32 v[32:33], v[32:33], v[130:131]
	v_lshlrev_b32_e32 v130, 16, v136
	v_and_b32_e32 v131, 0xffff0000, v136
	v_pk_mul_f32 v[26:27], v[26:27], v[130:131]
	v_lshlrev_b32_e32 v130, 16, v137
	v_and_b32_e32 v131, 0xffff0000, v137
	v_pk_mul_f32 v[28:29], v[28:29], v[130:131]
	s_waitcnt vmcnt(0)
; __device__ __forceinline__ unsigned pk_bf16(float lo, float hi) { const f32x2_t v = {lo, hi}; return __builtin_bit_cast(unsigned, __builtin_convertvector(v, bf16x2_t)); }
; __device__ __forceinline__ float bf_lo(unsigned w) { return __uint_as_float(w << 16); }
; __device__ __forceinline__ float bf_hi(unsigned w) { return __uint_as_float(w & 0xffff0000u); }
;     __device__ __forceinline__ bool operator()(f32x4 (&acc)[2][2][4][2], const Unit& u, int wr, int wc, int fr, int fq) const {
;     ...
;                 for (int bj = 0; bj < 2; ++bj) { const u32x4 s = *(const u32x4*)(S + off + bj * HALF);
;                     f32x4 v0 = acc[ai][bj][m][0], v1 = acc[ai][bj][m][1];
;                     v0[0] *= bf_lo(s.x); v0[1] *= bf_hi(s.x); v0[2] *= bf_lo(s.y); v0[3] *= bf_hi(s.y);
;                     v1[0] *= bf_lo(s.z); v1[1] *= bf_hi(s.z); v1[2] *= bf_lo(s.w); v1[3] *= bf_hi(s.w);
;                     acc[ai][bj][m][0] = v0; acc[ai][bj][m][1] = v1; } }
;         if (u.kh == 0) return false;
; #pragma unroll
;         for (int ai = 0; ai < 2; ++ai)
; #pragma unroll
;             for (int m = 0; m < 4; ++m) { const size_t off = (size_t)(r0 + ai * HALF + m * 16) * LDP + c0;
; #pragma unroll
;                 for (int bj = 0; bj < 2; ++bj) { const f32x4 v0 = acc[ai][bj][m][0], v1 = acc[ai][bj][m][1];
;                     u32x4 w; w.x = pk_bf16(v0[0], v0[1]); w.y = pk_bf16(v0[2], v0[3]); w.z = pk_bf16(v1[0], v1[1]); w.w = pk_bf16(v1[2], v1[3]);
;                     *(u32x4*)(MG + off + bj * HALF) = w; } }
	v_lshlrev_b32_e32 v130, 16, v178
	v_and_b32_e32 v131, 0xffff0000, v178
	v_pk_mul_f32 v[54:55], v[54:55], v[130:131]
	v_lshlrev_b32_e32 v130, 16, v179
	v_and_b32_e32 v131, 0xffff0000, v179
	v_pk_mul_f32 v[56:57], v[56:57], v[130:131]
	v_lshlrev_b32_e32 v130, 16, v180
	v_and_b32_e32 v131, 0xffff0000, v180
	v_pk_mul_f32 v[50:51], v[50:51], v[130:131]
	v_lshlrev_b32_e32 v130, 16, v181
	v_and_b32_e32 v131, 0xffff0000, v181
	v_pk_mul_f32 v[52:53], v[52:53], v[130:131]
	v_lshlrev_b32_e32 v130, 16, v182
	v_and_b32_e32 v131, 0xffff0000, v182
	v_pk_mul_f32 v[22:23], v[22:23], v[130:131]
	v_lshlrev_b32_e32 v130, 16, v183
	v_and_b32_e32 v131, 0xffff0000, v183
	v_pk_mul_f32 v[24:25], v[24:25], v[130:131]
	v_lshlrev_b32_e32 v130, 16, v184
	v_and_b32_e32 v131, 0xffff0000, v184
	v_pk_mul_f32 v[18:19], v[18:19], v[130:131]
	v_lshlrev_b32_e32 v130, 16, v185
	v_and_b32_e32 v131, 0xffff0000, v185
	v_pk_mul_f32 v[20:21], v[20:21], v[130:131]
	v_pk_mul_f32 v[122:123], v[122:123], v[204:205]
	v_lshlrev_b32_e32 v130, 16, v186
	v_and_b32_e32 v131, 0xffff0000, v186
	v_pk_mul_f32 v[46:47], v[46:47], v[130:131]
	v_lshlrev_b32_e32 v130, 16, v187
	v_and_b32_e32 v131, 0xffff0000, v187
	v_pk_mul_f32 v[48:49], v[48:49], v[130:131]
	v_lshlrev_b32_e32 v130, 16, v188
	v_and_b32_e32 v131, 0xffff0000, v188
	v_pk_mul_f32 v[42:43], v[42:43], v[130:131]
	v_lshlrev_b32_e32 v130, 16, v189
	v_and_b32_e32 v131, 0xffff0000, v189
	v_pk_mul_f32 v[44:45], v[44:45], v[130:131]
	v_lshlrev_b32_e32 v130, 16, v192
	v_and_b32_e32 v131, 0xffff0000, v192
	v_pk_mul_f32 v[14:15], v[14:15], v[130:131]
	v_lshlrev_b32_e32 v130, 16, v193
	v_and_b32_e32 v131, 0xffff0000, v193
	v_pk_mul_f32 v[16:17], v[16:17], v[130:131]
	v_lshlrev_b32_e32 v130, 16, v194
	v_and_b32_e32 v131, 0xffff0000, v194
	v_pk_mul_f32 v[10:11], v[10:11], v[130:131]
	v_lshlrev_b32_e32 v130, 16, v195
	v_and_b32_e32 v131, 0xffff0000, v195
	v_pk_mul_f32 v[12:13], v[12:13], v[130:131]
	v_lshlrev_b32_e32 v130, 16, v196
	v_and_b32_e32 v131, 0xffff0000, v196
	v_pk_mul_f32 v[38:39], v[38:39], v[130:131]
	v_lshlrev_b32_e32 v130, 16, v197
	v_and_b32_e32 v131, 0xffff0000, v197
	v_pk_mul_f32 v[40:41], v[40:41], v[130:131]
	v_lshlrev_b32_e32 v130, 16, v198
	v_and_b32_e32 v131, 0xffff0000, v198
	v_pk_mul_f32 v[34:35], v[34:35], v[130:131]
	v_lshlrev_b32_e32 v130, 16, v199
	v_and_b32_e32 v131, 0xffff0000, v199
	v_pk_mul_f32 v[36:37], v[36:37], v[130:131]
	v_lshlrev_b32_e32 v130, 16, v138
	v_and_b32_e32 v131, 0xffff0000, v138
	v_pk_mul_f32 v[6:7], v[6:7], v[130:131]
	v_lshlrev_b32_e32 v130, 16, v140
	v_and_b32_e32 v131, 0xffff0000, v140
	v_pk_mul_f32 v[94:95], v[94:95], v[206:207]
	v_pk_mul_f32 v[90:91], v[90:91], v[208:209]
	v_pk_mul_f32 v[118:119], v[118:119], v[210:211]
	v_pk_mul_f32 v[114:115], v[114:115], v[212:213]
	v_pk_mul_f32 v[86:87], v[86:87], v[214:215]
	v_pk_mul_f32 v[82:83], v[82:83], v[216:217]
	v_pk_mul_f32 v[66:67], v[66:67], v[170:171]
	v_pk_mul_f32 v[2:3], v[2:3], v[130:131]
	s_cbranch_scc0 .LBB0_904
	v_mov_b64_e32 v[136:137], s[12:13]
	v_mad_i64_i32 v[134:135], s[0:1], v160, s59, v[136:137]
	v_lshlrev_b64 v[158:159], 1, v[158:159]
	v_cvt_pk_bf16_f32 v130, v126, v127
	v_cvt_pk_bf16_f32 v131, v128, v129
	v_cvt_pk_bf16_f32 v132, v122, v123
	v_cvt_pk_bf16_f32 v133, v124, v125
	v_lshl_add_u64 v[134:135], v[134:135], 0, v[158:159]
	global_store_dwordx4 v[134:135], v[130:133], off
	s_mov_b64 s[40:41], -1
	s_nop 0
	v_cvt_pk_bf16_f32 v130, v94, v95
	v_cvt_pk_bf16_f32 v131, v96, v97
	v_cvt_pk_bf16_f32 v132, v90, v91
	v_cvt_pk_bf16_f32 v133, v92, v93
	global_store_dwordx4 v[134:135], v[130:133], off offset:256
	v_mad_i64_i32 v[134:135], s[0:1], v162, s59, v[136:137]
	s_nop 0
	v_cvt_pk_bf16_f32 v130, v118, v119
	v_cvt_pk_bf16_f32 v131, v120, v121
	v_cvt_pk_bf16_f32 v132, v114, v115
	v_cvt_pk_bf16_f32 v133, v116, v117
	v_lshl_add_u64 v[134:135], v[134:135], 0, v[158:159]
	global_store_dwordx4 v[134:135], v[130:133], off
	s_nop 1
	v_cvt_pk_bf16_f32 v130, v86, v87
	v_cvt_pk_bf16_f32 v131, v88, v89
	v_cvt_pk_bf16_f32 v132, v82, v83
	v_cvt_pk_bf16_f32 v133, v84, v85
	global_store_dwordx4 v[134:135], v[130:133], off offset:256
	v_mad_i64_i32 v[134:135], s[0:1], v164, s59, v[136:137]
	s_nop 0
	v_cvt_pk_bf16_f32 v130, v110, v111
	v_cvt_pk_bf16_f32 v131, v112, v113
	v_cvt_pk_bf16_f32 v132, v106, v107
	v_cvt_pk_bf16_f32 v133, v108, v109
	v_lshl_add_u64 v[134:135], v[134:135], 0, v[158:159]
	global_store_dwordx4 v[134:135], v[130:133], off
	s_nop 1
	v_cvt_pk_bf16_f32 v130, v78, v79
	v_cvt_pk_bf16_f32 v131, v80, v81
	v_cvt_pk_bf16_f32 v132, v74, v75
	v_cvt_pk_bf16_f32 v133, v76, v77
	global_store_dwordx4 v[134:135], v[130:133], off offset:256
	v_mad_i64_i32 v[134:135], s[0:1], v166, s59, v[136:137]
	s_nop 0
	v_cvt_pk_bf16_f32 v130, v102, v103
	v_cvt_pk_bf16_f32 v131, v104, v105
	v_cvt_pk_bf16_f32 v132, v98, v99
	v_cvt_pk_bf16_f32 v133, v100, v101
	v_lshl_add_u64 v[134:135], v[134:135], 0, v[158:159]
	global_store_dwordx4 v[134:135], v[130:133], off
	s_nop 1
	v_cvt_pk_bf16_f32 v130, v70, v71
	v_cvt_pk_bf16_f32 v131, v72, v73
	v_cvt_pk_bf16_f32 v132, v66, v67
	v_cvt_pk_bf16_f32 v133, v68, v69
	global_store_dwordx4 v[134:135], v[130:133], off offset:256
	v_mad_i64_i32 v[134:135], s[0:1], v168, s59, v[136:137]
	s_nop 0
	v_cvt_pk_bf16_f32 v130, v62, v63
	v_cvt_pk_bf16_f32 v131, v64, v65
	v_cvt_pk_bf16_f32 v132, v58, v59
	v_cvt_pk_bf16_f32 v133, v60, v61
	v_lshl_add_u64 v[134:135], v[134:135], 0, v[158:159]
	global_store_dwordx4 v[134:135], v[130:133], off
	s_nop 1
	v_cvt_pk_bf16_f32 v130, v30, v31
	v_cvt_pk_bf16_f32 v131, v32, v33
	v_cvt_pk_bf16_f32 v132, v26, v27
	v_cvt_pk_bf16_f32 v133, v28, v29
	global_store_dwordx4 v[134:135], v[130:133], off offset:256
	v_mad_i64_i32 v[134:135], s[0:1], v142, s59, v[136:137]
	s_nop 0
	v_cvt_pk_bf16_f32 v130, v54, v55
	v_cvt_pk_bf16_f32 v131, v56, v57
	v_cvt_pk_bf16_f32 v132, v50, v51
	v_cvt_pk_bf16_f32 v133, v52, v53
	v_lshl_add_u64 v[134:135], v[134:135], 0, v[158:159]
	global_store_dwordx4 v[134:135], v[130:133], off
	s_nop 1
	v_cvt_pk_bf16_f32 v130, v22, v23
	v_cvt_pk_bf16_f32 v131, v24, v25
	v_cvt_pk_bf16_f32 v132, v18, v19
	v_cvt_pk_bf16_f32 v133, v20, v21
	global_store_dwordx4 v[134:135], v[130:133], off offset:256
	v_mad_i64_i32 v[134:135], s[0:1], v144, s59, v[136:137]
	s_nop 0
	v_cvt_pk_bf16_f32 v130, v46, v47
	v_cvt_pk_bf16_f32 v131, v48, v49
	v_cvt_pk_bf16_f32 v132, v42, v43
	v_cvt_pk_bf16_f32 v133, v44, v45
	v_lshl_add_u64 v[134:135], v[134:135], 0, v[158:159]
	global_store_dwordx4 v[134:135], v[130:133], off
	s_nop 1
	v_cvt_pk_bf16_f32 v130, v14, v15
	v_cvt_pk_bf16_f32 v131, v16, v17
	v_cvt_pk_bf16_f32 v132, v10, v11
	v_cvt_pk_bf16_f32 v133, v12, v13
	global_store_dwordx4 v[134:135], v[130:133], off offset:256
	v_cvt_pk_bf16_f32 v134, v34, v35
	v_cvt_pk_bf16_f32 v135, v36, v37
	v_mad_i64_i32 v[130:131], s[0:1], v172, s59, v[136:137]
	v_cvt_pk_bf16_f32 v132, v38, v39
	v_cvt_pk_bf16_f32 v133, v40, v41
	v_lshl_add_u64 v[130:131], v[130:131], 0, v[158:159]
	global_store_dwordx4 v[130:131], v[132:135], off
